# out-projection residual epilogue: non-temporal hint on the streamed f32 residual loads and stores (same arithmetic)
# baseline (speedup 1.0000x reference)
.LBB0_881:
	s_ashr_i32 s12, s7, 3
	s_abs_i32 s13, s12
	s_mul_hi_u32 s14, s13, s3
	s_mul_i32 s15, s14, s10
	s_sub_i32 s13, s13, s15
	s_and_b32 s11, s7, 7
	s_ashr_i32 s7, s7, 31
	s_add_i32 s15, s14, 1
	s_sub_i32 s16, s13, s10
	s_cmp_ge_u32 s13, s10
	s_cselect_b32 s14, s15, s14
	s_cselect_b32 s13, s16, s13
	s_add_i32 s15, s14, 1
	s_cmp_ge_u32 s13, s10
	s_cselect_b32 s13, s15, s14
	s_xor_b32 s13, s13, s7
	s_sub_i32 s7, s13, s7
	s_mul_i32 s7, s7, s9
	s_sub_i32 s13, s8, s7
	s_min_i32 s13, s9, s13
	s_abs_i32 s15, s13
	v_cvt_f32_u32_e32 v62, s15
	s_sub_i32 s16, 0, s15
	s_lshl_b32 s14, s7, 3
	s_sub_i32 s12, s12, s14
	v_rcp_iflag_f32_e32 v62, v62
	s_abs_i32 s14, s12
	s_mul_i32 s11, s11, s8
	s_add_i32 s7, s7, s11
	v_mul_f32_e32 v62, 0x4f7ffffe, v62
	v_cvt_u32_f32_e32 v62, v62
	s_xor_b32 s11, s12, s13
	s_ashr_i32 s11, s11, 31
	v_mov_b32_e32 v76, v193
	v_readfirstlane_b32 s17, v62
	s_mul_i32 s16, s16, s17
	s_mul_hi_u32 s16, s17, s16
	s_add_i32 s17, s17, s16
	s_mul_hi_u32 s16, s14, s17
	s_mul_i32 s17, s16, s15
	s_sub_i32 s14, s14, s17
	s_add_i32 s17, s16, 1
	s_sub_i32 s18, s14, s15
	s_cmp_ge_u32 s14, s15
	s_cselect_b32 s16, s17, s16
	s_cselect_b32 s14, s18, s14
	s_add_i32 s17, s16, 1
	s_cmp_ge_u32 s14, s15
	s_cselect_b32 s14, s17, s16
	s_xor_b32 s14, s14, s11
	s_sub_i32 s11, s14, s11
	s_mul_i32 s13, s11, s13
	s_sub_i32 s12, s12, s13
	s_add_i32 s7, s7, s12
	s_lshl_b32 s12, s7, 7
	s_add_i32 s14, s12, 0xffffc000
	s_ashr_i32 s13, s12, 31
	s_cmpk_lt_i32 s7, 0x80
	s_cselect_b32 s12, s12, s14
	v_readlane_b32 s14, v253, 37
	v_readlane_b32 s15, v253, 39
	s_cselect_b32 s15, s14, s15
	v_readlane_b32 s14, v253, 38
	v_readlane_b32 s16, v253, 40
	s_cselect_b32 s14, s14, s16
	v_readlane_b32 s16, v253, 12
	s_cselect_b32 s13, s13, 0
	v_readlane_b32 s17, v253, 13
	v_readlane_b32 s30, v253, 26
	v_readlane_b32 s31, v253, 27
	s_cselect_b32 s16, s31, s39
	s_cselect_b32 s17, s30, s38
	s_lshl_b64 s[12:13], s[12:13], 12
	s_add_u32 s14, s14, s12
	s_addc_u32 s15, s15, s13
	s_add_u32 s12, s17, s12
	v_lshlrev_b32_e32 v62, 2, v76
	s_addc_u32 s13, s16, s13
	v_and_b32_e32 v62, 0x7c, v62
	s_min_i32 s7, s7, 0x80
	v_lshl_or_b32 v62, s11, 7, v62
	s_ashr_i32 s7, s7, 4
	v_readlane_b32 s11, v253, 41
	v_ashrrev_i32_e32 v63, 31, v62
	s_add_i32 s7, s7, s11
	v_lshlrev_b64 v[62:63], 2, v[62:63]
	s_mul_hi_i32 s11, s7, 0x3000
	s_mulk_i32 s7, 0x3000
	v_lshl_add_u64 v[72:73], s[12:13], 0, v[62:63]
	s_add_u32 s12, s48, s7
	s_addc_u32 s13, s49, s11
	v_ashrrev_i32_e32 v76, 5, v76
	v_lshl_add_u64 v[74:75], s[14:15], 0, v[62:63]
	v_lshl_add_u64 v[62:63], s[12:13], 0, v[62:63]
	s_mov_b32 s7, 0xa02000
	v_ashrrev_i32_e32 v77, 31, v76
	v_add_co_u32_e32 v62, vcc, s7, v62
	v_lshlrev_b64 v[76:77], 12, v[76:77]
	s_mov_b64 s[12:13], 0x8000
	s_mov_b64 s[60:61], 0x10000
	v_addc_co_u32_e32 v63, vcc, 0, v63, vcc
	v_lshl_add_u64 v[78:79], v[74:75], 0, v[76:77]
	v_lshl_add_u64 v[140:141], v[76:77], 0, s[12:13]
	global_load_dwordx4 v[62:65], v[62:63], off
	v_lshl_add_u64 v[82:83], v[74:75], 0, v[140:141]
	global_load_dwordx4 v[78:81], v[78:79], off nt
	v_lshl_add_u64 v[142:143], v[76:77], 0, s[60:61]
	s_mov_b64 s[12:13], 0x18000
	s_mov_b64 s[62:63], 0x20000
	global_load_dwordx4 v[82:85], v[82:83], off nt
	v_lshl_add_u64 v[86:87], v[74:75], 0, v[142:143]
	v_lshl_add_u64 v[144:145], v[76:77], 0, s[12:13]
	global_load_dwordx4 v[86:89], v[86:87], off nt
	v_lshl_add_u64 v[90:91], v[74:75], 0, v[144:145]
	v_lshl_add_u64 v[146:147], v[76:77], 0, s[62:63]
	s_mov_b64 s[12:13], 0x28000
	s_mov_b64 s[64:65], 0x30000
	global_load_dwordx4 v[90:93], v[90:91], off nt
	v_lshl_add_u64 v[94:95], v[74:75], 0, v[146:147]
	v_lshl_add_u64 v[148:149], v[76:77], 0, s[12:13]
	global_load_dwordx4 v[94:97], v[94:95], off nt
	v_lshl_add_u64 v[114:115], v[74:75], 0, v[148:149]
	v_lshl_add_u64 v[150:151], v[76:77], 0, s[64:65]
	s_mov_b64 s[12:13], 0x38000
	global_load_dwordx4 v[114:117], v[114:115], off nt
	v_lshl_add_u64 v[118:119], v[74:75], 0, v[150:151]
	v_lshl_add_u64 v[152:153], v[76:77], 0, s[12:13]
	global_load_dwordx4 v[118:121], v[118:119], off nt
	v_lshl_add_u64 v[136:137], v[74:75], 0, v[152:153]
	global_load_dwordx4 v[136:139], v[136:137], off nt
	s_mov_b64 s[12:13], 0x40000
	s_andn2_b64 vcc, exec, s[4:5]
	v_readlane_b32 s18, v253, 14
	v_readlane_b32 s19, v253, 15
	v_readlane_b32 s20, v253, 16
	v_readlane_b32 s21, v253, 17
	v_readlane_b32 s22, v253, 18
	v_readlane_b32 s23, v253, 19
	v_readlane_b32 s24, v253, 20
	v_readlane_b32 s25, v253, 21
	v_readlane_b32 s26, v253, 22
	v_readlane_b32 s27, v253, 23
	v_readlane_b32 s28, v253, 24
	v_readlane_b32 s29, v253, 25
	s_waitcnt vmcnt(0)
	v_pk_fma_f32 v[68:69], v[68:69], v[64:65], v[80:81]
	v_pk_fma_f32 v[66:67], v[66:67], v[62:63], v[78:79]
	v_lshl_add_u64 v[78:79], v[72:73], 0, v[76:77]
	global_store_dwordx4 v[78:79], v[66:69], off nt
	v_pk_fma_f32 v[60:61], v[60:61], v[64:65], v[84:85]
	v_pk_fma_f32 v[58:59], v[58:59], v[62:63], v[82:83]
	v_lshl_add_u64 v[66:67], v[72:73], 0, v[140:141]
	global_store_dwordx4 v[66:67], v[58:61], off nt
	v_pk_fma_f32 v[56:57], v[56:57], v[64:65], v[88:89]
	v_pk_fma_f32 v[54:55], v[54:55], v[62:63], v[86:87]
	v_lshl_add_u64 v[58:59], v[72:73], 0, v[142:143]
	global_store_dwordx4 v[58:59], v[54:57], off nt
	v_pk_fma_f32 v[52:53], v[52:53], v[64:65], v[92:93]
	v_pk_fma_f32 v[50:51], v[50:51], v[62:63], v[90:91]
	v_lshl_add_u64 v[54:55], v[72:73], 0, v[144:145]
	global_store_dwordx4 v[54:55], v[50:53], off nt
	v_pk_fma_f32 v[48:49], v[48:49], v[64:65], v[96:97]
	v_pk_fma_f32 v[46:47], v[46:47], v[62:63], v[94:95]
	v_lshl_add_u64 v[50:51], v[72:73], 0, v[146:147]
	global_store_dwordx4 v[50:51], v[46:49], off nt
	v_pk_fma_f32 v[44:45], v[44:45], v[64:65], v[116:117]
	v_pk_fma_f32 v[42:43], v[42:43], v[62:63], v[114:115]
	v_lshl_add_u64 v[46:47], v[72:73], 0, v[148:149]
	global_store_dwordx4 v[46:47], v[42:45], off nt
	v_pk_fma_f32 v[40:41], v[40:41], v[64:65], v[120:121]
	v_pk_fma_f32 v[38:39], v[38:39], v[62:63], v[118:119]
	v_lshl_add_u64 v[42:43], v[72:73], 0, v[150:151]
	global_store_dwordx4 v[42:43], v[38:41], off nt
	v_pk_fma_f32 v[36:37], v[36:37], v[64:65], v[138:139]
	v_pk_fma_f32 v[34:35], v[34:35], v[62:63], v[136:137]
	v_lshl_add_u64 v[38:39], v[72:73], 0, v[152:153]
	v_lshl_add_u64 v[78:79], v[76:77], 0, s[12:13]
	s_mov_b64 s[12:13], 0x48000
	global_store_dwordx4 v[38:39], v[34:37], off nt
	v_lshl_add_u64 v[80:81], v[76:77], 0, s[12:13]
	s_mov_b64 s[12:13], 0x50000
	v_lshl_add_u64 v[34:35], v[74:75], 0, v[78:79]
	global_load_dwordx4 v[34:37], v[34:35], off nt
	v_lshl_add_u64 v[38:39], v[74:75], 0, v[80:81]
	v_lshl_add_u64 v[82:83], v[76:77], 0, s[12:13]
	s_mov_b64 s[12:13], 0x58000
	global_load_dwordx4 v[38:41], v[38:39], off nt
	v_lshl_add_u64 v[42:43], v[74:75], 0, v[82:83]
	v_lshl_add_u64 v[84:85], v[76:77], 0, s[12:13]
	s_mov_b64 s[12:13], 0x60000
	global_load_dwordx4 v[42:45], v[42:43], off nt
	v_lshl_add_u64 v[46:47], v[74:75], 0, v[84:85]
	v_lshl_add_u64 v[86:87], v[76:77], 0, s[12:13]
	s_mov_b64 s[12:13], 0x68000
	global_load_dwordx4 v[46:49], v[46:47], off nt
	v_lshl_add_u64 v[50:51], v[74:75], 0, v[86:87]
	v_lshl_add_u64 v[88:89], v[76:77], 0, s[12:13]
	s_mov_b64 s[12:13], 0x70000
	global_load_dwordx4 v[50:53], v[50:51], off nt
	v_lshl_add_u64 v[54:55], v[74:75], 0, v[88:89]
	v_lshl_add_u64 v[90:91], v[76:77], 0, s[12:13]
	s_mov_b64 s[12:13], 0x78000
	global_load_dwordx4 v[54:57], v[54:55], off nt
	v_lshl_add_u64 v[58:59], v[74:75], 0, v[90:91]
	v_lshl_add_u64 v[76:77], v[76:77], 0, s[12:13]
	global_load_dwordx4 v[58:61], v[58:59], off nt
	v_lshl_add_u64 v[66:67], v[74:75], 0, v[76:77]
	global_load_dwordx4 v[66:69], v[66:67], off nt
	s_waitcnt vmcnt(0)
	v_pk_fma_f32 v[32:33], v[32:33], v[64:65], v[36:37]
	v_pk_fma_f32 v[30:31], v[30:31], v[62:63], v[34:35]
	v_lshl_add_u64 v[34:35], v[72:73], 0, v[78:79]
	global_store_dwordx4 v[34:35], v[30:33], off nt
	v_pk_fma_f32 v[28:29], v[28:29], v[64:65], v[40:41]
	v_pk_fma_f32 v[26:27], v[26:27], v[62:63], v[38:39]
	v_lshl_add_u64 v[30:31], v[72:73], 0, v[80:81]
	global_store_dwordx4 v[30:31], v[26:29], off nt
	v_pk_fma_f32 v[24:25], v[24:25], v[64:65], v[44:45]
	v_pk_fma_f32 v[22:23], v[22:23], v[62:63], v[42:43]
	v_lshl_add_u64 v[26:27], v[72:73], 0, v[82:83]
	global_store_dwordx4 v[26:27], v[22:25], off nt
	v_pk_fma_f32 v[20:21], v[20:21], v[64:65], v[48:49]
	v_pk_fma_f32 v[18:19], v[18:19], v[62:63], v[46:47]
	v_lshl_add_u64 v[22:23], v[72:73], 0, v[84:85]
	global_store_dwordx4 v[22:23], v[18:21], off nt
	v_pk_fma_f32 v[16:17], v[16:17], v[64:65], v[52:53]
	v_pk_fma_f32 v[14:15], v[14:15], v[62:63], v[50:51]
	v_lshl_add_u64 v[18:19], v[72:73], 0, v[86:87]
	global_store_dwordx4 v[18:19], v[14:17], off nt
	v_pk_fma_f32 v[12:13], v[12:13], v[64:65], v[56:57]
	v_pk_fma_f32 v[10:11], v[10:11], v[62:63], v[54:55]
	v_lshl_add_u64 v[14:15], v[72:73], 0, v[88:89]
	global_store_dwordx4 v[14:15], v[10:13], off nt
	v_pk_fma_f32 v[8:9], v[8:9], v[64:65], v[60:61]
	v_pk_fma_f32 v[6:7], v[6:7], v[62:63], v[58:59]
	v_lshl_add_u64 v[10:11], v[72:73], 0, v[90:91]
	global_store_dwordx4 v[10:11], v[6:9], off nt
	v_pk_fma_f32 v[4:5], v[4:5], v[64:65], v[68:69]
	v_pk_fma_f32 v[2:3], v[2:3], v[62:63], v[66:67]
	v_lshl_add_u64 v[6:7], v[72:73], 0, v[76:77]
	global_store_dwordx4 v[6:7], v[2:5], off nt
	s_cbranch_vccz .LBB0_888
